# LayerNorm rows assigned per XCD (XCD x normalises row panels 2208x..2208x+2207, matching the GEMM tile orders)
# speedup vs baseline: 1.0016x; 1.0016x over previous
; __device__ __forceinline__ int TID() { int t = threadIdx.x; asm volatile("" : "+v"(t)); return t; }
; __device__ __forceinline__ int BID() { int t = blockIdx.x; asm volatile("" : "+s"(t)); return t; }
; __device__ __forceinline__ void ln_phase(ArgsP a_, int lnidx, float cs, bool final_) { const ArgsP a = a_;
;     const int lane = TID() & 63, wv = TID() >> 6; const int gw = BID() * 8 + wv, nw = gridDim.x * 8;
;     bf16_t* HB = (bf16_t*)(a->ws + B_HB); const bf16_t* P0 = (const bf16_t*)(a->ws + B_PARTB); const bf16_t* P1 = P0 + (size_t)MP * 1024;
;     const float* g = AIN(7) + (size_t)lnidx * 1024; const float* bb = AIN(8) + (size_t)lnidx * 1024;
;     for (int row = gw; row < M_; row += nw) {
;         float z[16]; float s = 0.f;
; #pragma unroll
;         for (int q = 0; q < 2; ++q) { const size_t o = (size_t)row * 1024 + q * 512 + lane * 8; const u32x4 h = *(const u32x4*)(HB + o), p0 = *(const u32x4*)(P0 + o), p1 = *(const u32x4*)(P1 + o);
; #pragma unroll
;             for (int e = 0; e < 4; ++e) { const unsigned hh = h[e], a0 = p0[e], a1 = p1[e];
;                 z[q * 8 + 2 * e] = __uint_as_float(hh << 16) * ALPHA + (__uint_as_float(a0 << 16) + __uint_as_float(a1 << 16)) * cs;
;                 z[q * 8 + 2 * e + 1] = __uint_as_float(hh & 0xffff0000u) * ALPHA + (__uint_as_float(a0 & 0xffff0000u) + __uint_as_float(a1 & 0xffff0000u)) * cs; } }
; #pragma unroll
;         for (int e = 0; e < 16; ++e) s += z[e];
;         const float mean = wave_sum(s) * (1.f / 1024.f); float v = 0.f;
; #pragma unroll
;         for (int e = 0; e < 16; ++e) { const float d = z[e] - mean; v += d * d; }
;         const float rstd = rsqrtf(wave_sum(v) * (1.f / 1024.f) + LN_EPS);
;         float* yo = nullptr;
;         if (final_) { if (row < RP) { const int b = row / TP, t = row % TP; if (t >= 16) yo = a->out + O_YP + ((size_t)b * 2048 + t - 16) * 1024; } else yo = a->out + O_YS + (size_t)(row - RP) * 1024; }
; #pragma unroll
;         for (int q = 0; q < 2; ++q) { const int cc = q * 512 + lane * 8; const f32x4 g0 = *(const f32x4*)(g + cc), g1 = *(const f32x4*)(g + cc + 4), b0 = *(const f32x4*)(bb + cc), b1 = *(const f32x4*)(bb + cc + 4);
.LBB0_59:
	s_andn2_b64 vcc, exec, s[18:19]
	s_cbranch_vccnz .LBB0_89
	v_mov_b32_e32 v0, v186
	v_mov_b32_e32 v1, v186
	s_mov_b32 s13, s93
	v_ashrrev_i32_e32 v1, 6, v1
	s_nop 0
	s_and_b32 s98, s13, 7
	s_lshr_b32 s99, s13, 3
	v_lshl_add_u32 v12, s99, 3, v1
	s_mul_i32 s99, s98, 0x8a0
	v_add_u32_e32 v12, s99, v12
	s_add_i32 s98, s99, 0x89f
	s_min_i32 s98, s98, 0x447f
	s_movk_i32 s13, 0x4480
	v_cmp_gt_i32_e32 vcc, s13, v12
	s_and_saveexec_b64 s[18:19], vcc
	s_cbranch_execz .LBB0_88
	v_lshlrev_b32_e32 v0, 3, v0
	v_and_b32_e32 v14, 0x1f8, v0
	v_and_b32_e32 v0, 64, v188
	v_add_u32_e32 v0, 64, v0
	v_xor_b32_e32 v1, 32, v188
	v_cmp_lt_i32_e32 vcc, v1, v0
	v_readlane_b32 s13, v254, 60
	s_cmp_eq_u32 s13, 3
	v_cndmask_b32_e32 v1, v188, v1, vcc
	v_lshlrev_b32_e32 v36, 2, v1
	v_xor_b32_e32 v1, 16, v188
	v_cmp_lt_i32_e32 vcc, v1, v0
	s_cselect_b64 s[22:23], -1, 0
	s_cmp_lg_u32 s13, 3
	v_cndmask_b32_e32 v1, v188, v1, vcc
	s_cselect_b64 s[24:25], -1, 0
	s_waitcnt lgkmcnt(0)
	s_add_u32 s26, s2, 0xfd80000
	v_lshlrev_b32_e32 v37, 2, v1
	v_xor_b32_e32 v1, 8, v188
	s_addc_u32 s27, s3, 0
	v_cmp_lt_i32_e32 vcc, v1, v0
	s_add_u32 s34, s2, 0xb880000
	s_load_dwordx4 s[44:47], s[0:1], 0x38
	v_cndmask_b32_e32 v1, v188, v1, vcc
	s_addc_u32 s35, s3, 0
	v_lshlrev_b32_e32 v38, 2, v1
	v_xor_b32_e32 v1, 4, v188
	s_add_u32 s42, s2, 0xdb00000
	s_mul_i32 s13, s13, 3
	v_cmp_lt_i32_e32 vcc, v1, v0
	s_addc_u32 s43, s3, 0
	s_add_i32 s40, s13, 2
	s_mov_b32 s41, s12
	v_cndmask_b32_e32 v1, v188, v1, vcc
	s_lshl_b64 s[40:41], s[40:41], 12
	v_lshlrev_b32_e32 v39, 2, v1
	v_xor_b32_e32 v1, 2, v188
	s_waitcnt lgkmcnt(0)
	s_add_u32 s46, s46, s40
	v_cmp_lt_i32_e32 vcc, v1, v0
	s_addc_u32 s47, s47, s41
	s_add_u32 s40, s44, s40
	v_cndmask_b32_e32 v1, v188, v1, vcc
	v_lshlrev_b32_e32 v40, 2, v1
	v_xor_b32_e32 v1, 1, v188
	s_addc_u32 s41, s45, s41
	v_cmp_lt_i32_e32 vcc, v1, v0
	s_add_u32 s44, s2, 0x3752b700
	v_lshlrev_b32_e32 v16, 2, v14
	v_cndmask_b32_e32 v0, v188, v1, vcc
	v_mov_b32_e32 v15, v17
	v_lshlrev_b32_e32 v41, 2, v0
	s_addc_u32 s45, s3, 0
	v_lshl_add_u64 v[18:19], s[40:41], 0, v[16:17]
	v_lshl_add_u64 v[20:21], s[46:47], 0, v[16:17]
	s_mov_b64 s[46:47], 0
	global_load_dwordx4 v[214:217], v[18:19], off offset:16
	global_load_dwordx4 v[218:221], v[18:19], off
	global_load_dwordx4 v[222:225], v[20:21], off offset:16
	global_load_dwordx4 v[226:229], v[20:21], off
	global_load_dwordx4 v[230:233], v[18:19], off offset:2064
	global_load_dwordx4 v[234:237], v[18:19], off offset:2048
	global_load_dwordx4 v[238:241], v[20:21], off offset:2048
	global_load_dwordx4 v[242:245], v[20:21], off offset:2064
	s_waitcnt vmcnt(0)
	s_branch .LBB0_65

; __device__ __forceinline__ void ln_phase(ArgsP a_, int lnidx, float cs, bool final_) { const ArgsP a = a_;
;     ...
;     for (int row = gw; row < M_; row += nw) {
.LBB0_64:
	v_add_u32_e32 v12, 0x100, v12
	v_cmp_lt_i32_e32 vcc, s98, v12
	s_or_b64 s[46:47], vcc, s[46:47]
	s_andn2_b64 exec, exec, s[46:47]
	s_cbranch_execz .LBB0_88

; __device__ __forceinline__ int TID() { int t = threadIdx.x; asm volatile("" : "+v"(t)); return t; }
; __device__ __forceinline__ int BID() { int t = blockIdx.x; asm volatile("" : "+s"(t)); return t; }
; __device__ __forceinline__ void ln_phase(ArgsP a_, int lnidx, float cs, bool final_) { const ArgsP a = a_;
;     const int lane = TID() & 63, wv = TID() >> 6; const int gw = BID() * 8 + wv, nw = gridDim.x * 8;
;     bf16_t* HB = (bf16_t*)(a->ws + B_HB); const bf16_t* P0 = (const bf16_t*)(a->ws + B_PARTB); const bf16_t* P1 = P0 + (size_t)MP * 1024;
;     const float* g = AIN(7) + (size_t)lnidx * 1024; const float* bb = AIN(8) + (size_t)lnidx * 1024;
;     for (int row = gw; row < M_; row += nw) {
;         float z[16]; float s = 0.f;
; #pragma unroll
;         for (int q = 0; q < 2; ++q) { const size_t o = (size_t)row * 1024 + q * 512 + lane * 8; const u32x4 h = *(const u32x4*)(HB + o), p0 = *(const u32x4*)(P0 + o), p1 = *(const u32x4*)(P1 + o);
; #pragma unroll
;             for (int e = 0; e < 4; ++e) { const unsigned hh = h[e], a0 = p0[e], a1 = p1[e];
;                 z[q * 8 + 2 * e] = __uint_as_float(hh << 16) * ALPHA + (__uint_as_float(a0 << 16) + __uint_as_float(a1 << 16)) * cs;
;                 z[q * 8 + 2 * e + 1] = __uint_as_float(hh & 0xffff0000u) * ALPHA + (__uint_as_float(a0 & 0xffff0000u) + __uint_as_float(a1 & 0xffff0000u)) * cs; } }
.LBB0_91:
	v_writelane_b32 v255, s22, 1
	s_and_b64 vcc, exec, s[18:19]
	s_nop 0
	v_writelane_b32 v255, s23, 2
	s_cbranch_vccz .LBB0_99
	v_readlane_b32 s13, v254, 61
	s_cmp_gt_i32 s13, 6
	s_cbranch_scc0 .LBB0_101
	s_cmp_lt_i32 s13, 8
	s_mov_b64 s[56:57], -1
	s_cbranch_scc0 .LBB0_98
	v_mov_b32_e32 v10, v186
	v_mov_b32_e32 v0, v186
	s_mov_b32 s13, s93
	v_ashrrev_i32_e32 v0, 6, v0
	s_nop 0
	s_and_b32 s98, s13, 7
	s_lshr_b32 s99, s13, 3
	v_lshl_add_u32 v0, s99, 3, v0
	s_mul_i32 s99, s98, 0x8a0
	v_add_u32_e32 v0, s99, v0
	s_add_i32 s98, s99, 0x89f
	s_min_i32 s98, s98, 0x447f
	s_movk_i32 s13, 0x4480
	v_cmp_gt_i32_e32 vcc, s13, v0
	s_and_saveexec_b64 s[18:19], vcc
	s_mov_b32 s34, 0x3fd744fd
	v_readlane_b32 s42, v254, 49
	v_readlane_b32 s44, v254, 51
	s_mov_b32 s35, 0.5
	s_movk_i32 s40, 0x447f
	s_mov_b32 s41, 0x3752b000
	v_readlane_b32 s43, v254, 50
	v_readlane_b32 s45, v254, 52
	s_cbranch_execz .LBB0_97
	v_lshlrev_b32_e32 v1, 3, v10
	v_and_b32_e32 v8, 0x1f8, v1
	v_and_b32_e32 v1, 64, v188
	v_add_u32_e32 v1, 64, v1
	v_xor_b32_e32 v2, 32, v188
	v_cmp_lt_i32_e32 vcc, v2, v1
	s_load_dwordx4 s[24:27], s[0:1], 0x38
	v_readlane_b32 s13, v254, 60
	v_cndmask_b32_e32 v2, v188, v2, vcc
	v_lshlrev_b32_e32 v22, 2, v2
	v_xor_b32_e32 v2, 16, v188
	v_cmp_lt_i32_e32 vcc, v2, v1
	s_mul_i32 s13, s13, 3
	s_mov_b32 s23, s12
	v_cndmask_b32_e32 v2, v188, v2, vcc
	v_lshlrev_b32_e32 v23, 2, v2
	v_xor_b32_e32 v2, 8, v188
	v_cmp_lt_i32_e32 vcc, v2, v1
	s_add_i32 s22, s13, 1
	s_lshl_b64 s[22:23], s[22:23], 12
	v_cndmask_b32_e32 v2, v188, v2, vcc
	v_lshlrev_b32_e32 v24, 2, v2
	v_xor_b32_e32 v2, 4, v188
	v_cmp_lt_i32_e32 vcc, v2, v1
	s_waitcnt lgkmcnt(0)
	s_add_u32 s26, s26, s22
	s_addc_u32 s27, s27, s23
	v_cndmask_b32_e32 v2, v188, v2, vcc
	v_lshlrev_b32_e32 v25, 2, v2
	v_xor_b32_e32 v2, 2, v188
	v_cmp_lt_i32_e32 vcc, v2, v1
	s_add_u32 s22, s24, s22
	s_addc_u32 s23, s25, s23
	v_cndmask_b32_e32 v2, v188, v2, vcc
	v_lshlrev_b32_e32 v26, 2, v2
	v_xor_b32_e32 v2, 1, v188
	v_cmp_lt_i32_e32 vcc, v2, v1
	v_lshlrev_b32_e32 v16, 2, v8
	v_lshl_add_u64 v[4:5], s[26:27], 0, v[16:17]
	v_cndmask_b32_e32 v1, v188, v2, vcc
	v_lshlrev_b32_e32 v27, 2, v1
	v_ashrrev_i32_e32 v1, 31, v0
	v_lshlrev_b64 v[6:7], 10, v[0:1]
	v_or_b32_e32 v6, v6, v8
	v_lshlrev_b64 v[8:9], 11, v[0:1]
	v_and_b32_e32 v1, 63, v10
	v_lshl_add_u64 v[2:3], s[22:23], 0, v[16:17]
	v_lshl_or_b32 v8, v1, 4, v8
	s_mov_b64 s[22:23], 0
	global_load_dwordx4 v[214:217], v[2:3], off offset:16
	global_load_dwordx4 v[218:221], v[2:3], off
	global_load_dwordx4 v[222:225], v[4:5], off offset:16
	global_load_dwordx4 v[226:229], v[4:5], off
	global_load_dwordx4 v[230:233], v[2:3], off offset:2064
	global_load_dwordx4 v[234:237], v[2:3], off offset:2048
	global_load_dwordx4 v[238:241], v[4:5], off offset:2064
	global_load_dwordx4 v[242:245], v[4:5], off offset:2048
	s_waitcnt vmcnt(0)
	s_mov_b32 s42, 0x40000
	s_mov_b32 s43, 0
	s_mov_b32 s44, 0x80000
	s_mov_b32 s45, 0
.LBB0_96:
	v_lshl_add_u64 v[18:19], s[2:3], 0, v[8:9]
	v_add_co_u32_e32 v10, vcc, 0xfd80000, v18
	v_add_u32_e32 v0, 0x100, v0
	s_nop 0
	v_addc_co_u32_e32 v11, vcc, 0, v19, vcc
	v_add_co_u32_e32 v28, vcc, 0xb880000, v18
	global_load_dwordx4 v[12:15], v[10:11], off
	s_nop 0
	v_addc_co_u32_e32 v29, vcc, 0, v19, vcc
	v_add_co_u32_e32 v40, vcc, 0xdb00000, v18
	global_load_dwordx4 v[32:35], v[28:29], off
	s_nop 0
	v_addc_co_u32_e32 v41, vcc, 0, v19, vcc
	global_load_dwordx4 v[36:39], v[40:41], off
	global_load_dwordx4 v[202:205], v[10:11], off offset:1024
	global_load_dwordx4 v[206:209], v[28:29], off offset:1024
	global_load_dwordx4 v[210:213], v[40:41], off offset:1024
	v_lshl_add_u64 v[8:9], v[8:9], 0, s[44:45]
	s_waitcnt vmcnt(3)
	v_lshlrev_b32_e32 v1, 16, v12
	v_lshlrev_b32_e32 v16, 16, v32
	v_lshlrev_b32_e32 v18, 16, v36
	v_add_f32_e32 v18, v18, v16
	v_fmac_f32_e32 v18, 0x3fd744fd, v1
	v_and_b32_e32 v1, 0xffff0000, v12
	v_and_b32_e32 v12, 0xffff0000, v36
	v_and_b32_e32 v16, 0xffff0000, v32
	v_add_f32_e32 v19, v12, v16
	v_lshlrev_b32_e32 v12, 16, v33
	v_lshlrev_b32_e32 v16, 16, v37
	v_fmac_f32_e32 v19, 0x3fd744fd, v1
	v_lshlrev_b32_e32 v1, 16, v13
	v_add_f32_e32 v20, v16, v12
	v_fmac_f32_e32 v20, 0x3fd744fd, v1
	v_and_b32_e32 v1, 0xffff0000, v13
	v_and_b32_e32 v12, 0xffff0000, v37
	v_and_b32_e32 v13, 0xffff0000, v33
	v_add_f32_e32 v21, v12, v13
	v_lshlrev_b32_e32 v12, 16, v34
	v_lshlrev_b32_e32 v13, 16, v38
	v_fmac_f32_e32 v21, 0x3fd744fd, v1
	v_lshlrev_b32_e32 v1, 16, v14
	v_add_f32_e32 v31, v13, v12
	v_and_b32_e32 v12, 0xffff0000, v38
	v_and_b32_e32 v13, 0xffff0000, v34
	v_fmac_f32_e32 v31, 0x3fd744fd, v1
	v_and_b32_e32 v1, 0xffff0000, v14
	v_add_f32_e32 v32, v12, v13
	v_lshlrev_b32_e32 v12, 16, v35
	v_lshlrev_b32_e32 v13, 16, v39
	v_fmac_f32_e32 v32, 0x3fd744fd, v1
	v_lshlrev_b32_e32 v1, 16, v15
	v_add_f32_e32 v33, v13, v12
	v_and_b32_e32 v12, 0xffff0000, v39
	v_and_b32_e32 v13, 0xffff0000, v35
	v_fmac_f32_e32 v33, 0x3fd744fd, v1
	v_and_b32_e32 v1, 0xffff0000, v15
	v_add_f32_e32 v34, v12, v13
	s_nop 0
	v_add_f32_e32 v30, 0, v18
	v_add_f32_e32 v30, v19, v30
	v_fmac_f32_e32 v34, 0x3fd744fd, v1
	v_add_f32_e32 v30, v20, v30
	v_add_f32_e32 v30, v21, v30
	v_add_f32_e32 v30, v31, v30
	v_add_f32_e32 v30, v32, v30
	v_add_f32_e32 v30, v33, v30
	v_add_f32_e32 v30, v34, v30
	s_waitcnt vmcnt(2)
	v_lshlrev_b32_e32 v16, 16, v202
	s_waitcnt vmcnt(1)
	v_lshlrev_b32_e32 v1, 16, v206
	s_waitcnt vmcnt(0)
; __device__ __forceinline__ void ln_phase(ArgsP a_, int lnidx, float cs, bool final_) { const ArgsP a = a_;
;     ...
; #pragma unroll
;         for (int q = 0; q < 2; ++q) { const size_t o = (size_t)row * 1024 + q * 512 + lane * 8; const u32x4 h = *(const u32x4*)(HB + o), p0 = *(const u32x4*)(P0 + o), p1 = *(const u32x4*)(P1 + o);
; #pragma unroll
;             for (int e = 0; e < 4; ++e) { const unsigned hh = h[e], a0 = p0[e], a1 = p1[e];
;                 z[q * 8 + 2 * e] = __uint_as_float(hh << 16) * ALPHA + (__uint_as_float(a0 << 16) + __uint_as_float(a1 << 16)) * cs;
;                 z[q * 8 + 2 * e + 1] = __uint_as_float(hh & 0xffff0000u) * ALPHA + (__uint_as_float(a0 & 0xffff0000u) + __uint_as_float(a1 & 0xffff0000u)) * cs; } }
; #pragma unroll
;         for (int e = 0; e < 16; ++e) s += z[e];
;         const float mean = wave_sum(s) * (1.f / 1024.f); float v = 0.f;
; #pragma unroll
;         for (int e = 0; e < 16; ++e) { const float d = z[e] - mean; v += d * d; }
;         const float rstd = rsqrtf(wave_sum(v) * (1.f / 1024.f) + LN_EPS);
	v_lshlrev_b32_e32 v28, 16, v210
	v_add_f32_e32 v1, v28, v1
	v_fmac_f32_e32 v1, 0x3fd744fd, v16
	v_and_b32_e32 v16, 0xffff0000, v210
	v_and_b32_e32 v28, 0xffff0000, v206
	v_and_b32_e32 v12, 0xffff0000, v202
	v_add_f32_e32 v16, v16, v28
	v_lshlrev_b32_e32 v28, 16, v207
	v_lshlrev_b32_e32 v29, 16, v211
	v_fmac_f32_e32 v16, 0x3fd744fd, v12
	v_lshlrev_b32_e32 v12, 16, v203
	v_add_f32_e32 v28, v29, v28
	v_fmac_f32_e32 v28, 0x3fd744fd, v12
	v_and_b32_e32 v12, 0xffff0000, v203
	v_and_b32_e32 v13, 0xffff0000, v211
	v_and_b32_e32 v29, 0xffff0000, v207
	v_add_f32_e32 v29, v13, v29
	v_lshlrev_b32_e32 v41, 16, v213
	v_lshlrev_b32_e32 v45, 16, v209
	v_and_b32_e32 v40, 0xffff0000, v213
	v_and_b32_e32 v44, 0xffff0000, v209
	v_add_f32_e32 v30, v1, v30
	v_fmac_f32_e32 v29, 0x3fd744fd, v12
	v_lshlrev_b32_e32 v13, 16, v212
	v_lshlrev_b32_e32 v37, 16, v208
	v_and_b32_e32 v12, 0xffff0000, v212
	v_and_b32_e32 v36, 0xffff0000, v208
	v_add_f32_e32 v30, v16, v30
	v_and_b32_e32 v38, 0xffff0000, v205
	v_lshlrev_b32_e32 v39, 16, v205
	v_pk_add_f32 v[40:41], v[44:45], v[40:41]
	v_add_f32_e32 v30, v28, v30
	v_pk_fma_f32 v[38:39], v[38:39], s[34:35], v[40:41] op_sel_hi:[1,0,1]
	v_and_b32_e32 v40, 0xffff0000, v204
	v_lshlrev_b32_e32 v41, 16, v204
	v_pk_add_f32 v[12:13], v[36:37], v[12:13]
	v_add_f32_e32 v30, v29, v30
	v_pk_fma_f32 v[12:13], v[40:41], s[34:35], v[12:13] op_sel_hi:[1,0,1]
	s_nop 0
	v_add_f32_e32 v14, v13, v30
	v_add_f32_e32 v14, v12, v14
	v_add_f32_e32 v14, v39, v14
	v_add_f32_e32 v14, v38, v14
	ds_bpermute_b32 v15, v22, v14
	s_waitcnt lgkmcnt(0)
	v_add_f32_e32 v14, v14, v15
	ds_bpermute_b32 v15, v23, v14
	s_waitcnt lgkmcnt(0)
	v_add_f32_e32 v14, v14, v15
	ds_bpermute_b32 v15, v24, v14
	s_waitcnt lgkmcnt(0)
	v_add_f32_e32 v14, v14, v15
	ds_bpermute_b32 v15, v25, v14
	s_waitcnt lgkmcnt(0)
	v_add_f32_e32 v14, v14, v15
	ds_bpermute_b32 v15, v26, v14
	s_waitcnt lgkmcnt(0)
	v_add_f32_e32 v14, v14, v15
	ds_bpermute_b32 v15, v27, v14
	s_waitcnt lgkmcnt(0)
	v_add_f32_e32 v14, v14, v15
	v_fmac_f32_e32 v19, 0xba800000, v14
	v_fmac_f32_e32 v18, 0xba800000, v14
	v_mul_f32_e32 v35, v19, v19
	v_fmac_f32_e32 v35, v18, v18
	v_fmac_f32_e32 v20, 0xba800000, v14
	v_fmac_f32_e32 v35, v20, v20
	v_fmac_f32_e32 v21, 0xba800000, v14
	v_fmac_f32_e32 v35, v21, v21
	v_fmac_f32_e32 v31, 0xba800000, v14
	v_fmac_f32_e32 v35, v31, v31
	v_fmac_f32_e32 v32, 0xba800000, v14
	v_fmac_f32_e32 v35, v32, v32
	v_fmac_f32_e32 v33, 0xba800000, v14
	v_fmac_f32_e32 v35, v33, v33
	v_fmac_f32_e32 v34, 0xba800000, v14
	v_fmac_f32_e32 v35, v34, v34
	v_fmac_f32_e32 v1, 0xba800000, v14
	v_fmac_f32_e32 v35, v1, v1
	v_fmac_f32_e32 v16, 0xba800000, v14
	v_mul_f32_e32 v30, 0x3a800000, v14
	v_fmac_f32_e32 v35, v16, v16
	v_fmac_f32_e32 v28, 0xba800000, v14
	v_fmac_f32_e32 v35, v28, v28
	v_fmac_f32_e32 v29, 0xba800000, v14
	v_pk_add_f32 v[14:15], v[12:13], v[30:31] op_sel_hi:[1,0] neg_lo:[0,1] neg_hi:[0,1]
	v_fmac_f32_e32 v35, v29, v29
	v_pk_mul_f32 v[12:13], v[14:15], v[14:15]
	s_nop 0
	v_add_f32_e32 v13, v13, v35
	v_add_f32_e32 v35, v12, v13
	v_pk_add_f32 v[12:13], v[38:39], v[30:31] op_sel_hi:[1,0] neg_lo:[0,1] neg_hi:[0,1]
	s_nop 0
	v_pk_mul_f32 v[36:37], v[12:13], v[12:13]
	s_nop 0
	v_add_f32_e32 v30, v37, v35
	v_add_f32_e32 v30, v36, v30
	ds_bpermute_b32 v35, v22, v30
	s_waitcnt lgkmcnt(0)
	v_add_f32_e32 v30, v30, v35
	ds_bpermute_b32 v35, v23, v30
	s_waitcnt lgkmcnt(0)
	v_add_f32_e32 v30, v30, v35
	ds_bpermute_b32 v35, v24, v30
	s_waitcnt lgkmcnt(0)
	v_add_f32_e32 v30, v30, v35
	ds_bpermute_b32 v35, v25, v30
	s_waitcnt lgkmcnt(0)
	v_add_f32_e32 v30, v30, v35
	ds_bpermute_b32 v35, v26, v30
	s_waitcnt lgkmcnt(0)
; __device__ __forceinline__ unsigned cvt_pk_bf16(float lo, float hi) { unsigned r; asm("v_cvt_pk_bf16_f32 %0, %1, %2" : "=v"(r) : "v"(lo), "v"(hi)); return r; }
; __device__ __forceinline__ unsigned pk_fp8x4(float a, float b, float c, float d) { int w = 0; w = __builtin_amdgcn_cvt_pk_fp8_f32(clamp448(a), clamp448(b), w, false); w = __builtin_amdgcn_cvt_pk_fp8_f32(clamp448(c), clamp448(d), w, true); return (unsigned)w; }
; __device__ __forceinline__ void ln_phase(ArgsP a_, int lnidx, float cs, bool final_) { const ArgsP a = a_;
;     ...
;         const float rstd = rsqrtf(wave_sum(v) * (1.f / 1024.f) + LN_EPS);
;         float* yo = nullptr;
;         if (final_) { if (row < RP) { const int b = row / TP, t = row % TP; if (t >= 16) yo = a->out + O_YP + ((size_t)b * 2048 + t - 16) * 1024; } else yo = a->out + O_YS + (size_t)(row - RP) * 1024; }
; #pragma unroll
;         for (int q = 0; q < 2; ++q) { const int cc = q * 512 + lane * 8; const f32x4 g0 = *(const f32x4*)(g + cc), g1 = *(const f32x4*)(g + cc + 4), b0 = *(const f32x4*)(bb + cc), b1 = *(const f32x4*)(bb + cc + 4);
;             f32x4 o0, o1;
; #pragma unroll
;             for (int e = 0; e < 4; ++e) { o0[e] = (z[q * 8 + e] - mean) * rstd * g0[e] + b0[e]; o1[e] = (z[q * 8 + 4 + e] - mean) * rstd * g1[e] + b1[e]; }
;             if (final_) { if (yo) { *(f32x4*)(yo + cc) = o0; *(f32x4*)(yo + cc + 4) = o1; } }
;             else { *(u32x4*)(HB + (size_t)row * 1024 + cc) = (u32x4){cvt_pk_bf16(o0[0], o0[1]), cvt_pk_bf16(o0[2], o0[3]), cvt_pk_bf16(o1[0], o1[1]), cvt_pk_bf16(o1[2], o1[3])};
;                    *(u32x2*)(a->ws + B_HB8 + (size_t)row * 1024 + cc) = (u32x2){pk_fp8x4(o0[0] * SC_H, o0[1] * SC_H, o0[2] * SC_H, o0[3] * SC_H), pk_fp8x4(o1[0] * SC_H, o1[1] * SC_H, o1[2] * SC_H, o1[3] * SC_H)}; } }
	v_add_f32_e32 v30, v30, v35
	ds_bpermute_b32 v35, v27, v30
	s_waitcnt lgkmcnt(0)
	v_add_f32_e32 v30, v30, v35
	v_fmamk_f32 v30, v30, 0x3a800000, v187
	v_cmp_gt_f32_e32 vcc, s31, v30
	v_mul_f32_e32 v35, 0x4b800000, v30
	s_nop 0
	v_cndmask_b32_e32 v30, v30, v35, vcc
	v_rsq_f32_e32 v30, v30
	s_nop 0
	v_mul_f32_e32 v35, 0x45800000, v30
	v_cndmask_b32_e32 v30, v30, v35, vcc
	v_mul_f32_e32 v18, v18, v30
	v_mul_f32_e32 v15, v15, v30
	v_mul_f32_e32 v1, v1, v30
	v_mul_f32_e32 v14, v14, v30
	v_mul_f32_e32 v13, v13, v30
	v_mul_f32_e32 v12, v12, v30
	v_fma_f32 v35, v218, v18, v226
	v_mul_f32_e32 v18, v31, v30
	v_fma_f32 v31, v214, v18, v222
	v_mul_f32_e32 v18, v19, v30
	v_fma_f32 v36, v219, v18, v227
	v_mul_f32_e32 v18, v32, v30
	v_fma_f32 v32, v215, v18, v223
	v_mul_f32_e32 v18, v20, v30
	v_fma_f32 v37, v220, v18, v228
	v_mul_f32_e32 v18, v33, v30
	v_fma_f32 v33, v216, v18, v224
	v_mul_f32_e32 v18, v21, v30
	v_fma_f32 v51, v221, v18, v229
	v_mul_f32_e32 v18, v34, v30
	v_fma_f32 v47, v217, v18, v225
	v_cvt_pk_bf16_f32 v18, v35, v36
	v_cvt_pk_bf16_f32 v19, v37, v51
	v_cvt_pk_bf16_f32 v20, v31, v32
	v_cvt_pk_bf16_f32 v21, v33, v47
	global_store_dwordx4 v[10:11], v[18:21], off
	v_mul_f32_e32 v34, 0x4134cccd, v51
	s_nop 0
	v_mul_f32_e32 v18, 0x4134cccd, v35
	v_mul_f32_e32 v19, 0x4134cccd, v36
	v_med3_f32 v18, v18, s17, v190
	v_med3_f32 v19, v19, s17, v190
	v_mov_b32_e32 v20, v17
	v_cvt_pk_fp8_f32 v20, v18, v19
	v_mul_f32_e32 v21, 0x4134cccd, v37
	v_med3_f32 v18, v21, s17, v190
	v_med3_f32 v19, v34, s17, v190
	v_cvt_pk_fp8_f32 v20, v18, v19 op_sel:[0,0,1]
	v_mul_f32_e32 v18, 0x4134cccd, v31
	v_mul_f32_e32 v19, 0x4134cccd, v32
	v_med3_f32 v18, v18, s17, v190
	v_med3_f32 v19, v19, s17, v190
	v_mov_b32_e32 v21, v17
	v_cvt_pk_fp8_f32 v21, v18, v19
	v_mul_f32_e32 v31, 0x4134cccd, v33
	v_mul_f32_e32 v32, 0x4134cccd, v47
	v_med3_f32 v18, v31, s17, v190
	v_med3_f32 v19, v32, s17, v190
	v_cvt_pk_fp8_f32 v21, v18, v19 op_sel:[0,0,1]
	v_lshl_add_u64 v[18:19], s[2:3], 0, v[6:7]
	v_add_co_u32_e32 v18, vcc, s41, v18
	v_lshl_add_u64 v[6:7], v[6:7], 0, s[42:43]
	s_nop 0
	v_addc_co_u32_e32 v19, vcc, 0, v19, vcc
	global_store_dwordx2 v[18:19], v[20:21], off offset:1792
	v_cmp_lt_i32_e32 vcc, s98, v0
	s_or_b64 s[22:23], vcc, s[22:23]
	v_fma_f32 v20, v230, v15, v238
	v_mul_f32_e32 v15, v16, v30
	v_fma_f32 v1, v234, v1, v242
	v_fma_f32 v16, v235, v15, v243
	v_fma_f32 v21, v231, v14, v239
	v_mul_f32_e32 v14, v28, v30
	v_fma_f32 v31, v232, v13, v240
	v_mul_f32_e32 v13, v29, v30
	v_fma_f32 v28, v236, v14, v244
	v_fma_f32 v47, v237, v13, v245
	v_fma_f32 v43, v233, v12, v241
	v_cvt_pk_bf16_f32 v12, v1, v16
	v_cvt_pk_bf16_f32 v13, v28, v47
	v_cvt_pk_bf16_f32 v14, v20, v21
	v_cvt_pk_bf16_f32 v15, v31, v43
	global_store_dwordx4 v[10:11], v[12:15], off offset:1024
	v_mul_f32_e32 v1, 0x4134cccd, v1
	v_mul_f32_e32 v10, 0x4134cccd, v16
	v_med3_f32 v1, v1, s17, v190
	v_med3_f32 v13, v10, s17, v190
	v_mov_b32_e32 v10, v17
	v_cvt_pk_fp8_f32 v10, v1, v13
	v_mul_f32_e32 v11, 0x4134cccd, v28
	v_mul_f32_e32 v12, 0x4134cccd, v47
	v_med3_f32 v1, v11, s17, v190
	v_med3_f32 v11, v12, s17, v190
	v_cvt_pk_fp8_f32 v10, v1, v11 op_sel:[0,0,1]
	v_mul_f32_e32 v1, 0x4134cccd, v20
	v_mul_f32_e32 v11, 0x4134cccd, v21
	v_med3_f32 v1, v1, s17, v190
	v_med3_f32 v14, v11, s17, v190
	v_mov_b32_e32 v11, v17
	v_cvt_pk_fp8_f32 v11, v1, v14
	v_mul_f32_e32 v12, 0x4134cccd, v31
	v_mul_f32_e32 v13, 0x4134cccd, v43
	v_med3_f32 v1, v12, s17, v190
	v_med3_f32 v12, v13, s17, v190
	v_cvt_pk_fp8_f32 v11, v1, v12 op_sel:[0,0,1]
	global_store_dwordx2 v[18:19], v[10:11], off offset:2304
	s_andn2_b64 exec, exec, s[22:23]
	s_cbranch_execnz .LBB0_96

; __device__ __forceinline__ int TID() { int t = threadIdx.x; asm volatile("" : "+v"(t)); return t; }
; __device__ __forceinline__ int BID() { int t = blockIdx.x; asm volatile("" : "+s"(t)); return t; }
; __device__ __forceinline__ void ln_phase(ArgsP a_, int lnidx, float cs, bool final_) { const ArgsP a = a_;
;     const int lane = TID() & 63, wv = TID() >> 6; const int gw = BID() * 8 + wv, nw = gridDim.x * 8;
;     bf16_t* HB = (bf16_t*)(a->ws + B_HB); const bf16_t* P0 = (const bf16_t*)(a->ws + B_PARTB); const bf16_t* P1 = P0 + (size_t)MP * 1024;
;     const float* g = AIN(7) + (size_t)lnidx * 1024; const float* bb = AIN(8) + (size_t)lnidx * 1024;
;     for (int row = gw; row < M_; row += nw) {
;         float z[16]; float s = 0.f;
; #pragma unroll
;         for (int q = 0; q < 2; ++q) { const size_t o = (size_t)row * 1024 + q * 512 + lane * 8; const u32x4 h = *(const u32x4*)(HB + o), p0 = *(const u32x4*)(P0 + o), p1 = *(const u32x4*)(P1 + o);
; #pragma unroll
;             for (int e = 0; e < 4; ++e) { const unsigned hh = h[e], a0 = p0[e], a1 = p1[e];
;                 z[q * 8 + 2 * e] = __uint_as_float(hh << 16) * ALPHA + (__uint_as_float(a0 << 16) + __uint_as_float(a1 << 16)) * cs;
;                 z[q * 8 + 2 * e + 1] = __uint_as_float(hh & 0xffff0000u) * ALPHA + (__uint_as_float(a0 & 0xffff0000u) + __uint_as_float(a1 & 0xffff0000u)) * cs; } }
.LBB0_766:
	s_andn2_b64 vcc, exec, s[4:5]
	s_mov_b64 s[4:5], 0
	v_readlane_b32 s83, v254, 61
	s_cbranch_vccnz .LBB0_773
	v_readlane_b32 s18, v255, 1
	s_cmp_gt_i32 s83, 0
	s_mov_b64 s[4:5], -1
	s_mov_b32 s34, 0x3752b000
	v_readlane_b32 s68, v255, 3
	v_readlane_b32 s19, v255, 2
	s_cbranch_scc0 .LBB0_775
	s_cmp_gt_i32 s83, 1
	s_mov_b64 s[18:19], -1
	s_cbranch_scc0 .LBB0_1032
	v_mov_b32_e32 v10, v186
	v_mov_b32_e32 v0, v186
	s_mov_b32 s4, s93
	v_ashrrev_i32_e32 v0, 6, v0
	s_nop 0
	s_and_b32 s98, s4, 7
	s_lshr_b32 s99, s4, 3
	v_lshl_add_u32 v0, s99, 3, v0
	s_mul_i32 s99, s98, 0x8a0
	v_add_u32_e32 v0, s99, v0
	s_add_i32 s98, s99, 0x89f
	s_min_i32 s98, s98, 0x447f
	s_movk_i32 s4, 0x4480
	v_cmp_gt_i32_e32 vcc, s4, v0
	s_and_saveexec_b64 s[4:5], vcc
	s_mov_b32 s22, 0x3fd744fd
	v_readlane_b32 s40, v254, 49
	v_readlane_b32 s42, v254, 51
	s_mov_b32 s23, 0.5
	s_movk_i32 s13, 0x447f
	v_readlane_b32 s41, v254, 50
	v_readlane_b32 s43, v254, 52
	s_cbranch_execz .LBB0_772
	v_lshlrev_b32_e32 v1, 3, v10
	v_and_b32_e32 v8, 0x1f8, v1
	v_and_b32_e32 v1, 64, v188
	v_add_u32_e32 v1, 64, v1
	v_xor_b32_e32 v2, 32, v188
	v_cmp_lt_i32_e32 vcc, v2, v1
	s_load_dwordx4 s[24:27], s[0:1], 0x38
	v_readlane_b32 s0, v254, 60
	v_cndmask_b32_e32 v2, v188, v2, vcc
	v_lshlrev_b32_e32 v22, 2, v2
	v_xor_b32_e32 v2, 16, v188
	v_cmp_lt_i32_e32 vcc, v2, v1
	s_mul_i32 s0, s0, 3
	s_mov_b32 s1, s12
	v_cndmask_b32_e32 v2, v188, v2, vcc
	v_lshlrev_b32_e32 v23, 2, v2
	v_xor_b32_e32 v2, 8, v188
	v_cmp_lt_i32_e32 vcc, v2, v1
	s_lshl_b64 s[0:1], s[0:1], 12
	s_waitcnt lgkmcnt(0)
	s_add_u32 s18, s26, s0
	v_cndmask_b32_e32 v2, v188, v2, vcc
	v_lshlrev_b32_e32 v24, 2, v2
	v_xor_b32_e32 v2, 4, v188
	v_cmp_lt_i32_e32 vcc, v2, v1
	s_addc_u32 s19, s27, s1
	s_add_u32 s0, s24, s0
	v_cndmask_b32_e32 v2, v188, v2, vcc
	v_lshlrev_b32_e32 v25, 2, v2
	v_xor_b32_e32 v2, 2, v188
	v_cmp_lt_i32_e32 vcc, v2, v1
	s_addc_u32 s1, s25, s1
	v_lshlrev_b32_e32 v16, 2, v8
	v_cndmask_b32_e32 v2, v188, v2, vcc
	v_lshlrev_b32_e32 v26, 2, v2
	v_xor_b32_e32 v2, 1, v188
	v_cmp_lt_i32_e32 vcc, v2, v1
	v_lshl_add_u64 v[4:5], s[18:19], 0, v[16:17]
	s_nop 0
	v_cndmask_b32_e32 v1, v188, v2, vcc
	v_lshlrev_b32_e32 v27, 2, v1
	v_ashrrev_i32_e32 v1, 31, v0
	v_lshlrev_b64 v[6:7], 10, v[0:1]
	v_or_b32_e32 v6, v6, v8
	v_lshlrev_b64 v[8:9], 11, v[0:1]
	v_and_b32_e32 v1, 63, v10
	v_lshl_add_u64 v[2:3], s[0:1], 0, v[16:17]
	v_lshl_or_b32 v8, v1, 4, v8
	s_mov_b64 s[0:1], 0
	global_load_dwordx4 v[214:217], v[2:3], off offset:16
	global_load_dwordx4 v[218:221], v[2:3], off
	global_load_dwordx4 v[222:225], v[4:5], off offset:16
	global_load_dwordx4 v[226:229], v[4:5], off
	global_load_dwordx4 v[230:233], v[2:3], off offset:2064
	global_load_dwordx4 v[234:237], v[2:3], off offset:2048
	global_load_dwordx4 v[238:241], v[4:5], off offset:2064
	global_load_dwordx4 v[242:245], v[4:5], off offset:2048
	s_waitcnt vmcnt(0)
	s_mov_b32 s40, 0x40000
	s_mov_b32 s41, 0
	s_mov_b32 s42, 0x80000
	s_mov_b32 s43, 0
.LBB0_771:
	v_lshl_add_u64 v[18:19], s[2:3], 0, v[8:9]
	v_add_co_u32_e32 v10, vcc, 0xfd80000, v18
	v_add_u32_e32 v0, 0x100, v0
	s_nop 0
	v_addc_co_u32_e32 v11, vcc, 0, v19, vcc
	v_add_co_u32_e32 v28, vcc, 0xb880000, v18
	global_load_dwordx4 v[12:15], v[10:11], off
	s_nop 0
	v_addc_co_u32_e32 v29, vcc, 0, v19, vcc
	v_add_co_u32_e32 v40, vcc, 0xdb00000, v18
	global_load_dwordx4 v[32:35], v[28:29], off
	s_nop 0
	v_addc_co_u32_e32 v41, vcc, 0, v19, vcc
	global_load_dwordx4 v[36:39], v[40:41], off
	global_load_dwordx4 v[202:205], v[10:11], off offset:1024
	global_load_dwordx4 v[206:209], v[28:29], off offset:1024
	global_load_dwordx4 v[210:213], v[40:41], off offset:1024
	v_lshl_add_u64 v[8:9], v[8:9], 0, s[42:43]
	s_waitcnt vmcnt(3)
	v_lshlrev_b32_e32 v18, 16, v12
	v_and_b32_e32 v20, 0xffff0000, v12
	v_and_b32_e32 v30, 0xffff0000, v32
	v_lshlrev_b32_e32 v16, 16, v32
	v_lshlrev_b32_e32 v12, 16, v33
	v_and_b32_e32 v31, 0xffff0000, v36
	v_lshlrev_b32_e32 v1, 16, v36
	v_pk_add_f32 v[30:31], v[30:31], v[30:31] op_sel_hi:[0,1]
	v_add_f32_e32 v19, v16, v1
	v_mov_b32_e32 v21, v31
	v_and_b32_e32 v31, 0xffff0000, v37
	v_and_b32_e32 v30, 0xffff0000, v33
	v_pk_mul_f32 v[18:19], v[18:19], s[22:23]
	v_pk_mul_f32 v[20:21], v[20:21], s[22:23]
	v_lshlrev_b32_e32 v1, 16, v37
	v_pk_add_f32 v[30:31], v[30:31], v[30:31] op_sel_hi:[0,1]
	v_add_f32_e32 v18, v18, v19
	v_add_f32_e32 v19, v20, v21
	v_lshlrev_b32_e32 v20, 16, v13
	v_add_f32_e32 v21, v12, v1
	v_and_b32_e32 v12, 0xffff0000, v13
	v_mov_b32_e32 v13, v31
	v_pk_mul_f32 v[20:21], v[20:21], s[22:23]
	v_pk_mul_f32 v[12:13], v[12:13], s[22:23]
	v_add_f32_e32 v20, v20, v21
	v_add_f32_e32 v21, v12, v13
	v_lshlrev_b32_e32 v1, 16, v38
	v_lshlrev_b32_e32 v13, 16, v34
	v_lshlrev_b32_e32 v12, 16, v14
	v_add_f32_e32 v13, v13, v1
	v_and_b32_e32 v33, 0xffff0000, v38
	v_and_b32_e32 v32, 0xffff0000, v34
	v_pk_mul_f32 v[12:13], v[12:13], s[22:23]
	v_pk_add_f32 v[32:33], v[32:33], v[32:33] op_sel_hi:[0,1]
	v_add_f32_e32 v31, v12, v13
	v_and_b32_e32 v12, 0xffff0000, v14
	v_mov_b32_e32 v13, v33
	v_pk_mul_f32 v[12:13], v[12:13], s[22:23]
	v_lshlrev_b32_e32 v1, 16, v39
	v_add_f32_e32 v32, v12, v13
	v_lshlrev_b32_e32 v13, 16, v35
	v_lshlrev_b32_e32 v12, 16, v15
	v_add_f32_e32 v13, v13, v1
	v_pk_mul_f32 v[12:13], v[12:13], s[22:23]
	v_and_b32_e32 v14, 0xffff0000, v35
	v_add_f32_e32 v33, v12, v13
	v_and_b32_e32 v12, 0xffff0000, v15
	v_and_b32_e32 v15, 0xffff0000, v39
	v_pk_add_f32 v[14:15], v[14:15], v[14:15] op_sel_hi:[0,1]
	v_mov_b32_e32 v13, v15
	v_pk_mul_f32 v[12:13], v[12:13], s[22:23]
	s_nop 0
	v_add_f32_e32 v34, v12, v13
	s_nop 0
	s_waitcnt vmcnt(2)
	v_lshlrev_b32_e32 v28, 16, v202
	s_waitcnt vmcnt(1)
	v_lshlrev_b32_e32 v16, 16, v206
	s_waitcnt vmcnt(0)
; __device__ __forceinline__ void ln_phase(ArgsP a_, int lnidx, float cs, bool final_) { const ArgsP a = a_;
;     ...
; #pragma unroll
;         for (int q = 0; q < 2; ++q) { const size_t o = (size_t)row * 1024 + q * 512 + lane * 8; const u32x4 h = *(const u32x4*)(HB + o), p0 = *(const u32x4*)(P0 + o), p1 = *(const u32x4*)(P1 + o);
; #pragma unroll
;             for (int e = 0; e < 4; ++e) { const unsigned hh = h[e], a0 = p0[e], a1 = p1[e];
;                 z[q * 8 + 2 * e] = __uint_as_float(hh << 16) * ALPHA + (__uint_as_float(a0 << 16) + __uint_as_float(a1 << 16)) * cs;
;                 z[q * 8 + 2 * e + 1] = __uint_as_float(hh & 0xffff0000u) * ALPHA + (__uint_as_float(a0 & 0xffff0000u) + __uint_as_float(a1 & 0xffff0000u)) * cs; } }
; #pragma unroll
;         for (int e = 0; e < 16; ++e) s += z[e];
;         const float mean = wave_sum(s) * (1.f / 1024.f); float v = 0.f;
; #pragma unroll
;         for (int e = 0; e < 16; ++e) { const float d = z[e] - mean; v += d * d; }
;         const float rstd = rsqrtf(wave_sum(v) * (1.f / 1024.f) + LN_EPS);
	v_lshlrev_b32_e32 v1, 16, v210
	v_add_f32_e32 v29, v16, v1
	v_and_b32_e32 v45, 0xffff0000, v210
	v_and_b32_e32 v44, 0xffff0000, v206
	v_pk_mul_f32 v[28:29], v[28:29], s[22:23]
	v_pk_add_f32 v[44:45], v[44:45], v[44:45] op_sel_hi:[0,1]
	v_add_f32_e32 v1, v28, v29
	v_and_b32_e32 v28, 0xffff0000, v202
	v_mov_b32_e32 v29, v45
	v_pk_mul_f32 v[28:29], v[28:29], s[22:23]
	v_lshlrev_b32_e32 v12, 16, v211
	v_and_b32_e32 v41, 0xffff0000, v211
	v_and_b32_e32 v40, 0xffff0000, v207
	v_add_f32_e32 v16, v28, v29
	v_lshlrev_b32_e32 v29, 16, v207
	v_pk_add_f32 v[36:37], v[40:41], v[40:41] op_sel_hi:[0,1]
	v_lshlrev_b32_e32 v28, 16, v203
	v_add_f32_e32 v29, v29, v12
	v_and_b32_e32 v12, 0xffff0000, v203
	v_mov_b32_e32 v13, v37
	v_pk_mul_f32 v[28:29], v[28:29], s[22:23]
	v_pk_mul_f32 v[12:13], v[12:13], s[22:23]
	v_add_f32_e32 v28, v28, v29
	v_add_f32_e32 v29, v12, v13
	v_lshlrev_b32_e32 v13, 16, v212
	v_lshlrev_b32_e32 v30, 16, v208
	v_and_b32_e32 v41, 0xffff0000, v212
	v_and_b32_e32 v40, 0xffff0000, v208
	v_lshlrev_b32_e32 v12, 16, v204
	v_add_f32_e32 v13, v30, v13
	v_and_b32_e32 v36, 0xffff0000, v204
	v_pk_add_f32 v[40:41], v[40:41], v[40:41] op_sel_hi:[0,1]
	v_lshlrev_b32_e32 v14, 16, v213
	v_lshlrev_b32_e32 v30, 16, v209
	v_mov_b32_e32 v37, v41
	v_add_f32_e32 v41, v30, v14
	v_add_f32_e32 v30, 0, v18
	v_add_f32_e32 v30, v19, v30
	v_add_f32_e32 v30, v20, v30
	v_add_f32_e32 v30, v21, v30
	v_add_f32_e32 v30, v31, v30
	v_add_f32_e32 v30, v32, v30
	v_and_b32_e32 v43, 0xffff0000, v213
	v_and_b32_e32 v42, 0xffff0000, v209
	v_add_f32_e32 v30, v33, v30
	v_pk_add_f32 v[38:39], v[42:43], v[42:43] op_sel_hi:[0,1]
	v_add_f32_e32 v30, v34, v30
	v_lshlrev_b32_e32 v40, 16, v205
	v_and_b32_e32 v14, 0xffff0000, v205
	v_mov_b32_e32 v15, v39
	v_add_f32_e32 v30, v1, v30
	v_pk_mul_f32 v[12:13], v[12:13], s[22:23]
	v_pk_mul_f32 v[36:37], v[36:37], s[22:23]
	v_pk_mul_f32 v[40:41], v[40:41], s[22:23]
	v_pk_mul_f32 v[14:15], v[14:15], s[22:23]
	v_add_f32_e32 v30, v16, v30
	v_add_f32_e32 v30, v28, v30
	v_mov_b32_e32 v38, v14
	v_mov_b32_e32 v39, v40
	v_mov_b32_e32 v40, v15
	v_mov_b32_e32 v14, v36
	v_mov_b32_e32 v15, v12
	v_mov_b32_e32 v12, v37
	v_add_f32_e32 v30, v29, v30
	v_pk_add_f32 v[12:13], v[14:15], v[12:13]
	v_pk_add_f32 v[38:39], v[38:39], v[40:41]
	v_add_f32_e32 v14, v13, v30
	v_add_f32_e32 v14, v12, v14
	v_add_f32_e32 v14, v39, v14
	v_add_f32_e32 v14, v38, v14
	ds_bpermute_b32 v15, v22, v14
	s_waitcnt lgkmcnt(0)
	v_add_f32_e32 v14, v14, v15
	ds_bpermute_b32 v15, v23, v14
	s_waitcnt lgkmcnt(0)
	v_add_f32_e32 v14, v14, v15
	ds_bpermute_b32 v15, v24, v14
	s_waitcnt lgkmcnt(0)
	v_add_f32_e32 v14, v14, v15
	ds_bpermute_b32 v15, v25, v14
	s_waitcnt lgkmcnt(0)
	v_add_f32_e32 v14, v14, v15
	ds_bpermute_b32 v15, v26, v14
	s_waitcnt lgkmcnt(0)
	v_add_f32_e32 v14, v14, v15
	ds_bpermute_b32 v15, v27, v14
	s_waitcnt lgkmcnt(0)
	v_add_f32_e32 v14, v14, v15
	v_fmac_f32_e32 v19, 0xba800000, v14
	v_fmac_f32_e32 v18, 0xba800000, v14
	v_mul_f32_e32 v35, v19, v19
	v_fmac_f32_e32 v35, v18, v18
	v_fmac_f32_e32 v20, 0xba800000, v14
	v_fmac_f32_e32 v35, v20, v20
	v_fmac_f32_e32 v21, 0xba800000, v14
	v_fmac_f32_e32 v35, v21, v21
	v_fmac_f32_e32 v31, 0xba800000, v14
	v_fmac_f32_e32 v35, v31, v31
	v_fmac_f32_e32 v32, 0xba800000, v14
	v_fmac_f32_e32 v35, v32, v32
	v_fmac_f32_e32 v33, 0xba800000, v14
	v_fmac_f32_e32 v35, v33, v33
	v_fmac_f32_e32 v34, 0xba800000, v14
	v_fmac_f32_e32 v35, v34, v34
	v_fmac_f32_e32 v1, 0xba800000, v14
	v_fmac_f32_e32 v35, v1, v1
	v_fmac_f32_e32 v16, 0xba800000, v14
	v_mul_f32_e32 v30, 0x3a800000, v14
	v_fmac_f32_e32 v35, v16, v16
	v_fmac_f32_e32 v28, 0xba800000, v14
	v_fmac_f32_e32 v35, v28, v28
	v_fmac_f32_e32 v29, 0xba800000, v14
	v_pk_add_f32 v[14:15], v[12:13], v[30:31] op_sel_hi:[1,0] neg_lo:[0,1] neg_hi:[0,1]
	v_fmac_f32_e32 v35, v29, v29
	v_pk_mul_f32 v[12:13], v[14:15], v[14:15]
	s_nop 0
	v_add_f32_e32 v13, v13, v35
	v_add_f32_e32 v35, v12, v13
	v_pk_add_f32 v[12:13], v[38:39], v[30:31] op_sel_hi:[1,0] neg_lo:[0,1] neg_hi:[0,1]
	s_nop 0
	v_pk_mul_f32 v[36:37], v[12:13], v[12:13]
	s_nop 0
	v_add_f32_e32 v30, v37, v35
	v_add_f32_e32 v30, v36, v30
	ds_bpermute_b32 v35, v22, v30
	s_waitcnt lgkmcnt(0)
; __device__ __forceinline__ unsigned cvt_pk_bf16(float lo, float hi) { unsigned r; asm("v_cvt_pk_bf16_f32 %0, %1, %2" : "=v"(r) : "v"(lo), "v"(hi)); return r; }
; __device__ __forceinline__ unsigned pk_fp8x4(float a, float b, float c, float d) { int w = 0; w = __builtin_amdgcn_cvt_pk_fp8_f32(clamp448(a), clamp448(b), w, false); w = __builtin_amdgcn_cvt_pk_fp8_f32(clamp448(c), clamp448(d), w, true); return (unsigned)w; }
; __device__ __forceinline__ void ln_phase(ArgsP a_, int lnidx, float cs, bool final_) { const ArgsP a = a_;
;     ...
;         const float rstd = rsqrtf(wave_sum(v) * (1.f / 1024.f) + LN_EPS);
;         float* yo = nullptr;
;         if (final_) { if (row < RP) { const int b = row / TP, t = row % TP; if (t >= 16) yo = a->out + O_YP + ((size_t)b * 2048 + t - 16) * 1024; } else yo = a->out + O_YS + (size_t)(row - RP) * 1024; }
; #pragma unroll
;         for (int q = 0; q < 2; ++q) { const int cc = q * 512 + lane * 8; const f32x4 g0 = *(const f32x4*)(g + cc), g1 = *(const f32x4*)(g + cc + 4), b0 = *(const f32x4*)(bb + cc), b1 = *(const f32x4*)(bb + cc + 4);
;             f32x4 o0, o1;
; #pragma unroll
;             for (int e = 0; e < 4; ++e) { o0[e] = (z[q * 8 + e] - mean) * rstd * g0[e] + b0[e]; o1[e] = (z[q * 8 + 4 + e] - mean) * rstd * g1[e] + b1[e]; }
;             if (final_) { if (yo) { *(f32x4*)(yo + cc) = o0; *(f32x4*)(yo + cc + 4) = o1; } }
;             else { *(u32x4*)(HB + (size_t)row * 1024 + cc) = (u32x4){cvt_pk_bf16(o0[0], o0[1]), cvt_pk_bf16(o0[2], o0[3]), cvt_pk_bf16(o1[0], o1[1]), cvt_pk_bf16(o1[2], o1[3])};
;                    *(u32x2*)(a->ws + B_HB8 + (size_t)row * 1024 + cc) = (u32x2){pk_fp8x4(o0[0] * SC_H, o0[1] * SC_H, o0[2] * SC_H, o0[3] * SC_H), pk_fp8x4(o1[0] * SC_H, o1[1] * SC_H, o1[2] * SC_H, o1[3] * SC_H)}; } }
	v_add_f32_e32 v30, v30, v35
	ds_bpermute_b32 v35, v23, v30
	s_waitcnt lgkmcnt(0)
	v_add_f32_e32 v30, v30, v35
	ds_bpermute_b32 v35, v24, v30
	s_waitcnt lgkmcnt(0)
	v_add_f32_e32 v30, v30, v35
	ds_bpermute_b32 v35, v25, v30
	s_waitcnt lgkmcnt(0)
	v_add_f32_e32 v30, v30, v35
	ds_bpermute_b32 v35, v26, v30
	s_waitcnt lgkmcnt(0)
	v_add_f32_e32 v30, v30, v35
	ds_bpermute_b32 v35, v27, v30
	s_waitcnt lgkmcnt(0)
	v_add_f32_e32 v30, v30, v35
	v_fmamk_f32 v30, v30, 0x3a800000, v187
	v_cmp_gt_f32_e32 vcc, s31, v30
	v_mul_f32_e32 v35, 0x4b800000, v30
	s_nop 0
	v_cndmask_b32_e32 v30, v30, v35, vcc
	v_rsq_f32_e32 v30, v30
	s_nop 0
	v_mul_f32_e32 v35, 0x45800000, v30
	v_cndmask_b32_e32 v30, v30, v35, vcc
	v_mul_f32_e32 v18, v18, v30
	v_mul_f32_e32 v15, v15, v30
	v_mul_f32_e32 v1, v1, v30
	v_mul_f32_e32 v14, v14, v30
	v_mul_f32_e32 v13, v13, v30
	v_mul_f32_e32 v12, v12, v30
	v_fma_f32 v35, v218, v18, v226
	v_mul_f32_e32 v18, v31, v30
	v_fma_f32 v31, v214, v18, v222
	v_mul_f32_e32 v18, v19, v30
	v_fma_f32 v36, v219, v18, v227
	v_mul_f32_e32 v18, v32, v30
	v_fma_f32 v32, v215, v18, v223
	v_mul_f32_e32 v18, v20, v30
	v_fma_f32 v37, v220, v18, v228
	v_mul_f32_e32 v18, v33, v30
	v_fma_f32 v33, v216, v18, v224
	v_mul_f32_e32 v18, v21, v30
	v_fma_f32 v51, v221, v18, v229
	v_mul_f32_e32 v18, v34, v30
	v_fma_f32 v47, v217, v18, v225
	v_cvt_pk_bf16_f32 v18, v35, v36
	v_cvt_pk_bf16_f32 v19, v37, v51
	v_cvt_pk_bf16_f32 v20, v31, v32
	v_cvt_pk_bf16_f32 v21, v33, v47
	global_store_dwordx4 v[10:11], v[18:21], off
	v_mul_f32_e32 v34, 0x4134cccd, v51
	s_nop 0
	v_mul_f32_e32 v18, 0x4134cccd, v35
	v_mul_f32_e32 v19, 0x4134cccd, v36
	v_med3_f32 v18, v18, s17, v190
	v_med3_f32 v19, v19, s17, v190
	v_mov_b32_e32 v20, v17
	v_cvt_pk_fp8_f32 v20, v18, v19
	v_mul_f32_e32 v21, 0x4134cccd, v37
	v_med3_f32 v18, v21, s17, v190
	v_med3_f32 v19, v34, s17, v190
	v_cvt_pk_fp8_f32 v20, v18, v19 op_sel:[0,0,1]
	v_mul_f32_e32 v18, 0x4134cccd, v31
	v_mul_f32_e32 v19, 0x4134cccd, v32
	v_med3_f32 v18, v18, s17, v190
	v_med3_f32 v19, v19, s17, v190
	v_mov_b32_e32 v21, v17
	v_cvt_pk_fp8_f32 v21, v18, v19
	v_mul_f32_e32 v31, 0x4134cccd, v33
	v_mul_f32_e32 v32, 0x4134cccd, v47
	v_med3_f32 v18, v31, s17, v190
	v_med3_f32 v19, v32, s17, v190
	v_cvt_pk_fp8_f32 v21, v18, v19 op_sel:[0,0,1]
	v_lshl_add_u64 v[18:19], s[2:3], 0, v[6:7]
	v_add_co_u32_e32 v18, vcc, s34, v18
	v_lshl_add_u64 v[6:7], v[6:7], 0, s[40:41]
	s_nop 0
	v_addc_co_u32_e32 v19, vcc, 0, v19, vcc
	v_cmp_lt_i32_e32 vcc, s98, v0
	s_or_b64 s[0:1], vcc, s[0:1]
	v_fma_f32 v20, v230, v15, v238
	v_mul_f32_e32 v15, v16, v30
	v_fma_f32 v1, v234, v1, v242
	v_fma_f32 v16, v235, v15, v243
	v_fma_f32 v21, v231, v14, v239
	v_mul_f32_e32 v14, v28, v30
	v_fma_f32 v31, v232, v13, v240
	v_mul_f32_e32 v13, v29, v30
	v_fma_f32 v28, v236, v14, v244
	v_fma_f32 v47, v237, v13, v245
	v_fma_f32 v43, v233, v12, v241
	v_cvt_pk_bf16_f32 v12, v1, v16
	v_cvt_pk_bf16_f32 v13, v28, v47
	v_cvt_pk_bf16_f32 v14, v20, v21
	v_cvt_pk_bf16_f32 v15, v31, v43
	global_store_dwordx4 v[10:11], v[12:15], off offset:1024
	v_mul_f32_e32 v1, 0x4134cccd, v1
	v_mul_f32_e32 v10, 0x4134cccd, v16
	v_med3_f32 v1, v1, s17, v190
	v_med3_f32 v13, v10, s17, v190
	v_mov_b32_e32 v10, v17
	v_cvt_pk_fp8_f32 v10, v1, v13
	v_mul_f32_e32 v11, 0x4134cccd, v28
	v_mul_f32_e32 v12, 0x4134cccd, v47
	v_med3_f32 v1, v11, s17, v190
	v_med3_f32 v11, v12, s17, v190
	v_cvt_pk_fp8_f32 v10, v1, v11 op_sel:[0,0,1]
	v_mul_f32_e32 v1, 0x4134cccd, v20
	v_mul_f32_e32 v11, 0x4134cccd, v21
	v_med3_f32 v1, v1, s17, v190
	v_med3_f32 v14, v11, s17, v190
	v_mov_b32_e32 v11, v17
	v_cvt_pk_fp8_f32 v11, v1, v14
	v_mul_f32_e32 v12, 0x4134cccd, v31
	v_mul_f32_e32 v13, 0x4134cccd, v43
	v_med3_f32 v1, v12, s17, v190
	v_med3_f32 v12, v13, s17, v190
	v_cvt_pk_fp8_f32 v11, v1, v12 op_sel:[0,0,1]
	s_andn2_b64 exec, exec, s[0:1]
	s_cbranch_execnz .LBB0_771
